# v15 + static s_setprio 1 for waves 4-7 during attention phase P5
# baseline (speedup 1.0000x reference)
.LBB0_909:
	v_writelane_b32 v245, s87, 33
	v_writelane_b32 v245, s92, 34
	s_nop 1
	v_writelane_b32 v245, s93, 35
	v_writelane_b32 v245, s88, 36
	s_nop 1
	v_writelane_b32 v245, s89, 37
	v_writelane_b32 v245, s90, 38
	v_writelane_b32 v245, s91, 39
	v_writelane_b32 v245, s84, 40
	s_nop 1
	v_writelane_b32 v245, s85, 41
	v_writelane_b32 v245, s80, 42
	s_nop 1
	v_writelane_b32 v245, s81, 43
	v_writelane_b32 v245, s67, 44
	v_writelane_b32 v245, s78, 45
	s_nop 1
	v_writelane_b32 v245, s79, 46
	v_writelane_b32 v245, s76, 47
	s_nop 1
	v_writelane_b32 v245, s77, 48
	v_writelane_b32 v245, s74, 49
	s_nop 1
	v_writelane_b32 v245, s75, 50
	s_or_b64 exec, exec, s[2:3]
	v_writelane_b32 v245, s88, 51
	s_add_u32 s0, s72, 0x3a500000
	s_waitcnt lgkmcnt(0)
	v_writelane_b32 v245, s89, 52
	v_writelane_b32 v245, s0, 53
	v_writelane_b32 v245, s72, 54
	s_addc_u32 s0, s73, 0
	s_barrier
	v_writelane_b32 v245, s73, 55
	v_writelane_b32 v245, s0, 56
	s_mov_b32 s0, 12
	s_ashr_i32 s1, s0, 31
	s_lshl_b64 s[0:1], s[0:1], 3
	s_add_u32 s0, s70, s0
	s_addc_u32 s1, s71, s1
	s_load_dwordx2 s[0:1], s[0:1], 0x0
	v_lshlrev_b32_e32 v2, 2, v177
	s_mov_b32 s2, 15
	v_mbcnt_hi_u32_b32 v6, -1, v1
	v_and_b32_e32 v1, 64, v6
	s_waitcnt lgkmcnt(0)
	global_load_dword v3, v2, s[0:1]
	s_mov_b32 s0, 13
	s_ashr_i32 s1, s0, 31
	s_lshl_b64 s[0:1], s[0:1], 3
	s_add_u32 s0, s70, s0
	s_addc_u32 s1, s71, s1
	s_load_dwordx2 s[0:1], s[0:1], 0x0
	v_xor_b32_e32 v7, 1, v6
	v_add_u32_e32 v8, 64, v1
	v_cmp_lt_i32_e32 vcc, v7, v8
	v_xor_b32_e32 v9, 2, v6
	s_waitcnt lgkmcnt(0)
	global_load_dword v4, v2, s[0:1]
	s_mov_b32 s0, 14
	s_ashr_i32 s1, s0, 31
	s_lshl_b64 s[0:1], s[0:1], 3
	s_add_u32 s0, s70, s0
	s_addc_u32 s1, s71, s1
	s_load_dwordx2 s[0:1], s[0:1], 0x0
	v_cndmask_b32_e32 v1, v6, v7, vcc
	v_lshlrev_b32_e32 v1, 2, v1
	v_cmp_lt_i32_e32 vcc, v9, v8
	s_waitcnt lgkmcnt(0)
	global_load_dword v5, v2, s[0:1]
	s_ashr_i32 s3, s2, 31
	s_lshl_b64 s[0:1], s[2:3], 3
	s_add_u32 s0, s70, s0
	v_writelane_b32 v245, s70, 57
	s_addc_u32 s1, s71, s1
	s_load_dwordx2 s[0:1], s[0:1], 0x0
	v_cndmask_b32_e32 v9, v6, v9, vcc
	v_lshlrev_b32_e32 v201, 2, v9
	v_writelane_b32 v245, s71, 58
	s_waitcnt lgkmcnt(0)
	global_load_dword v2, v2, s[0:1]
	s_mov_b32 s0, 0
	v_writelane_b32 v245, s0, 59
	v_writelane_b32 v245, s82, 60
	s_cmpk_gt_i32 s82, 0xff
	s_waitcnt vmcnt(2)
	v_mul_f32_e32 v7, v3, v4
	ds_bpermute_b32 v7, v1, v7
	v_writelane_b32 v245, s83, 61
	s_waitcnt lgkmcnt(0)
	v_fmac_f32_e32 v7, v3, v4
	ds_bpermute_b32 v3, v201, v7
	v_xor_b32_e32 v4, 4, v6
	v_cmp_lt_i32_e32 vcc, v4, v8
	s_waitcnt lgkmcnt(0)
	v_add_f32_e32 v3, v7, v3
	v_cndmask_b32_e32 v4, v6, v4, vcc
	v_lshlrev_b32_e32 v205, 2, v4
	ds_bpermute_b32 v4, v205, v3
	s_waitcnt lgkmcnt(0)
	v_add_f32_e32 v3, v3, v4
	v_xor_b32_e32 v4, 8, v6
	v_cmp_lt_i32_e32 vcc, v4, v8
	s_waitcnt vmcnt(0)
	v_mul_f32_e32 v7, v5, v2
	ds_bpermute_b32 v7, v1, v7
	v_cndmask_b32_e32 v4, v6, v4, vcc
	v_lshlrev_b32_e32 v211, 2, v4
	ds_bpermute_b32 v4, v211, v3
	s_waitcnt lgkmcnt(1)
	v_fmac_f32_e32 v7, v5, v2
	ds_bpermute_b32 v2, v201, v7
	s_waitcnt lgkmcnt(1)
	v_add_f32_e32 v3, v3, v4
	v_xor_b32_e32 v4, 16, v6
	v_cmp_lt_i32_e32 vcc, v4, v8
	s_waitcnt lgkmcnt(0)
	v_add_f32_e32 v2, v7, v2
	ds_bpermute_b32 v5, v205, v2
	v_cndmask_b32_e32 v4, v6, v4, vcc
	v_lshlrev_b32_e32 v218, 2, v4
	ds_bpermute_b32 v4, v218, v3
	s_waitcnt lgkmcnt(1)
	v_add_f32_e32 v5, v2, v5
	ds_bpermute_b32 v7, v211, v5
	s_waitcnt lgkmcnt(1)
	v_add_f32_e32 v2, v3, v4
	v_xor_b32_e32 v3, 32, v6
	v_cmp_lt_i32_e32 vcc, v3, v8
	s_waitcnt lgkmcnt(0)
	v_add_f32_e32 v4, v5, v7
	ds_bpermute_b32 v5, v218, v4
	v_cndmask_b32_e32 v3, v6, v3, vcc
	v_lshlrev_b32_e32 v219, 2, v3
	ds_bpermute_b32 v3, v219, v2
	s_waitcnt lgkmcnt(1)
	v_add_f32_e32 v4, v4, v5
	ds_bpermute_b32 v5, v219, v4
	s_cbranch_scc1 .LBB0_994
	v_readlane_b32 s4, v245, 60
	v_readlane_b32 s5, v245, 61
	s_lshl_b64 s[0:1], s[4:5], 17
	v_readlane_b32 s2, v245, 54
	v_readlane_b32 s3, v245, 55
	s_add_u32 s0, s2, s0
	s_waitcnt lgkmcnt(1)
	v_add_f32_e32 v2, v2, v3
	s_waitcnt lgkmcnt(0)
	v_add_f32_e32 v3, v4, v5
	s_addc_u32 s1, s3, s1
	v_mul_f32_e32 v2, 0x3fb8aa3b, v2
	v_mul_f32_e32 v3, 0x3fb8aa3b, v3
	s_add_u32 s0, s0, 0x1500000
	v_exp_f32_e32 v2, v2
	v_exp_f32_e32 v3, v3
	s_addc_u32 s1, s1, 0
	v_writelane_b32 v245, s0, 62
	s_mov_b32 s5, 0
	v_sub_f32_e32 v2, v2, v3
	v_writelane_b32 v245, s1, 63
	v_add_f32_e32 v200, 0x3e4ccccd, v2
	v_readlane_b32 s0, v245, 33
	s_lshl_b32 s0, s0, 5
	v_mov_b32_e32 v3, 0
	v_writelane_b32 v244, s0, 0
	s_mov_b32 s90, 0x1fffff0
	s_mov_b64 s[84:85], 0x2000
	s_movk_i32 s93, 0x118
	s_mov_b32 s91, 0x41380000
	v_mov_b32_e32 v202, 0x358637bd
	v_mov_b32_e32 v203, -1
	s_mov_b32 s87, 0x2b800000
	v_mov_b32_e32 v204, 0xff800000
	s_mov_b32 s1, s4
	v_writelane_b32 v244, s86, 1
	v_readfirstlane_b32 s98, v0
	s_nop 3
	s_bitcmp1_b32 s98, 8
	s_cbranch_scc0 .Lprio5_skip
	s_setprio 1
.Lprio5_skip:
.LBB0_911:
	s_and_b32 s0, s1, 15
	v_writelane_b32 v244, s1, 2
	s_bfe_u32 s1, s1, 0x40004
	v_writelane_b32 v244, s1, 3
	s_xor_b32 s1, s1, 31
	v_writelane_b32 v244, s1, 4
	s_lshl_b32 s1, s0, 20
	v_writelane_b32 v244, s1, 5
	s_lshl_b32 s1, s0, 21
	v_readlane_b32 s2, v245, 14
	v_readlane_b32 s3, v245, 15
	s_add_u32 s1, s2, s1
	s_addc_u32 s2, s3, 0
	s_add_u32 s74, s1, 0x2000000
	s_addc_u32 s75, s2, 0
	v_writelane_b32 v244, s1, 6
	s_add_u32 s76, s1, 0x4000000
	v_writelane_b32 v244, s2, 7
	s_addc_u32 s77, s2, 0
	s_lshl_b32 s0, s0, 14
	v_readlane_b32 s1, v244, 0
	s_add_i32 s0, s0, s1
	s_mov_b64 s[2:3], -1
	v_writelane_b32 v244, s0, 8
	s_branch .LBB0_913

.LBB0_994:
	s_setprio 0
	s_mov_b32 s0, 7
	s_ashr_i32 s1, s0, 31
	s_lshl_b64 s[0:1], s[0:1], 3
	v_readlane_b32 s68, v245, 57
	v_readlane_b32 s69, v245, 58
	s_add_u32 s0, s68, s0
	s_addc_u32 s1, s69, s1
	s_load_dwordx2 s[6:7], s[0:1], 0x0
	s_mov_b32 s0, 22
	s_ashr_i32 s1, s0, 31
	s_lshl_b64 s[0:1], s[0:1], 3
	s_add_u32 s0, s68, s0
	s_addc_u32 s1, s69, s1
	s_load_dwordx2 s[8:9], s[0:1], 0x0
	s_mov_b32 s0, 10
	s_ashr_i32 s1, s0, 31
	s_lshl_b64 s[0:1], s[0:1], 3
	s_add_u32 s0, s68, s0
	s_addc_u32 s1, s69, s1
	s_load_dwordx2 s[12:13], s[0:1], 0x0
	s_mov_b32 s0, 11
	s_ashr_i32 s1, s0, 31
	s_lshl_b64 s[0:1], s[0:1], 3
	s_add_u32 s0, s68, s0
	s_addc_u32 s1, s69, s1
	s_load_dwordx2 s[14:15], s[0:1], 0x0
	s_mov_b32 s0, 21
	s_ashr_i32 s1, s0, 31
	s_lshl_b64 s[0:1], s[0:1], 3
	s_add_u32 s0, s68, s0
	s_addc_u32 s1, s69, s1
	s_load_dwordx2 s[16:17], s[0:1], 0x0
	s_mov_b32 s0, 23
	s_ashr_i32 s1, s0, 31
	s_lshl_b64 s[0:1], s[0:1], 3
	s_add_u32 s0, s68, s0
	s_addc_u32 s1, s69, s1
	s_load_dwordx2 s[18:19], s[0:1], 0x0
	s_mov_b32 s0, 26
	s_ashr_i32 s1, s0, 31
	s_lshl_b64 s[0:1], s[0:1], 3
	s_add_u32 s0, s68, s0
	s_addc_u32 s1, s69, s1
	s_load_dwordx2 s[20:21], s[0:1], 0x0
	s_mov_b32 s0, 27
	s_ashr_i32 s1, s0, 31
	s_lshl_b64 s[0:1], s[0:1], 3
	s_add_u32 s0, s68, s0
	s_addc_u32 s1, s69, s1
	s_load_dwordx2 s[22:23], s[0:1], 0x0
	s_mov_b32 s0, 28
	s_ashr_i32 s1, s0, 31
	s_lshl_b64 s[0:1], s[0:1], 3
	s_add_u32 s0, s68, s0
	s_addc_u32 s1, s69, s1
	s_load_dwordx2 s[24:25], s[0:1], 0x0
	s_mov_b32 s0, 8
	s_ashr_i32 s1, s0, 31
	s_lshl_b64 s[0:1], s[0:1], 3
	s_add_u32 s0, s68, s0
	s_addc_u32 s1, s69, s1
	s_load_dwordx2 s[26:27], s[0:1], 0x0
	s_mov_b32 s0, 18
	s_ashr_i32 s1, s0, 31
	s_lshl_b64 s[0:1], s[0:1], 3
	s_add_u32 s0, s68, s0
	s_addc_u32 s1, s69, s1
	v_mov_b32_e32 v2, v0
	s_load_dwordx2 s[28:29], s[0:1], 0x0
	v_readlane_b32 s88, v245, 36
	v_cmp_ne_u32_e64 s[10:11], 0, v2
	s_waitcnt lgkmcnt(0)
	v_lshlrev_b32_e32 v3, 2, v2
	v_bfe_u32 v131, v2, 3, 3
	v_bfe_u32 v133, v2, 2, 4
	v_and_b32_e32 v4, 7, v2
	v_lshlrev_b32_e32 v2, 4, v2
	v_and_b32_e32 v130, 60, v3
	v_and_b32_e32 v137, 12, v133
	v_readlane_b32 s1, v245, 20
	v_and_b32_e32 v138, 48, v2
	v_readlane_b32 s72, v245, 49
	v_readlane_b32 s89, v245, 37
	v_mov_b32_e32 v135, 0
	v_add_u32_e32 v3, s1, v137
	s_movk_i32 s0, 0x84
	v_lshl_add_u32 v5, v4, 4, s1
	v_lshlrev_b32_e32 v136, 3, v4
	v_mul_u32_u24_e32 v4, 0x84, v131
	v_mul_u32_u24_e32 v6, 0x44, v130
	v_add_u32_e32 v2, s1, v138
	v_mul_u32_u24_e32 v7, 0x44, v133
	v_readlane_b32 s70, v245, 54
	v_readlane_b32 s73, v245, 50
	v_readlane_b32 s76, v245, 45
	v_readlane_b32 s80, v245, 42
	v_readlane_b32 s82, v245, 60
	v_readlane_b32 s84, v245, 40
	v_readlane_b32 s88, v245, 51
	v_readlane_b32 s92, v245, 34
	v_and_b32_e32 v132, 6, v131
	v_mad_u32_u24 v167, v130, s0, v3
	v_or_b32_e32 v169, 8, v131
	v_or_b32_e32 v171, 16, v131
	v_or_b32_e32 v173, 24, v131
	v_or_b32_e32 v175, 32, v131
	v_or_b32_e32 v177, 40, v131
	v_or_b32_e32 v179, 48, v131
	v_or_b32_e32 v181, 56, v131
	v_mov_b32_e32 v139, v135
	v_or_b32_e32 v189, 16, v133
	v_or_b32_e32 v193, 32, v133
	v_or_b32_e32 v197, 48, v133
	s_mov_b64 s[30:31], 0
	s_movk_i32 s0, 0x7bff
	s_movk_i32 s1, 0x37ff
	s_movk_i32 s52, 0x3bff
	s_movk_i32 s53, 0x6bff
	s_movk_i32 s54, 0x7dff
	s_movk_i32 s55, 0x7fff
	s_mov_b32 s56, 0xb7ff
	s_mov_b32 s57, 0xefff
	v_add_u32_e32 v220, v3, v6
	v_add_u32_e32 v221, v2, v7
	v_add_u32_e32 v222, v5, v4
	v_readlane_b32 s71, v245, 55
	v_readlane_b32 s74, v245, 47
	v_readlane_b32 s77, v245, 46
	v_readlane_b32 s78, v245, 44
	v_readlane_b32 s81, v245, 43
	v_readlane_b32 s83, v245, 61
	v_readlane_b32 s85, v245, 41
	v_readlane_b32 s90, v245, 38
	v_readlane_b32 s91, v245, 39
	v_readlane_b32 s89, v245, 52
	v_readlane_b32 s93, v245, 35
	v_readlane_b32 s73, v245, 25
	v_readlane_b32 s79, v245, 33
	v_readlane_b32 s75, v245, 48
	s_branch .LBB0_996

	.amdhsa_kernel _Z8mega_fwd4Args
		.amdhsa_group_segment_fixed_size 0
		.amdhsa_private_segment_fixed_size 0
		.amdhsa_kernarg_size 552
		.amdhsa_user_sgpr_count 2
		.amdhsa_user_sgpr_dispatch_ptr 0
		.amdhsa_user_sgpr_queue_ptr 0
		.amdhsa_user_sgpr_kernarg_segment_ptr 1
		.amdhsa_user_sgpr_dispatch_id 0
		.amdhsa_user_sgpr_kernarg_preload_length 0
		.amdhsa_user_sgpr_kernarg_preload_offset 0
		.amdhsa_user_sgpr_private_segment_size 0
		.amdhsa_uses_dynamic_stack 0
		.amdhsa_enable_private_segment 0
		.amdhsa_system_sgpr_workgroup_id_x 1
		.amdhsa_system_sgpr_workgroup_id_y 0
		.amdhsa_system_sgpr_workgroup_id_z 0
		.amdhsa_system_sgpr_workgroup_info 0
		.amdhsa_system_vgpr_workitem_id 0
		.amdhsa_next_free_vgpr 246
		.amdhsa_next_free_sgpr 102
		.amdhsa_accum_offset 248
		.amdhsa_reserve_vcc 1
		.amdhsa_float_round_mode_32 0
		.amdhsa_float_round_mode_16_64 0
		.amdhsa_float_denorm_mode_32 3
		.amdhsa_float_denorm_mode_16_64 3
		.amdhsa_dx10_clamp 1
		.amdhsa_ieee_mode 1
		.amdhsa_fp16_overflow 0
		.amdhsa_tg_split 0
		.amdhsa_exception_fp_ieee_invalid_op 0
		.amdhsa_exception_fp_denorm_src 0
		.amdhsa_exception_fp_ieee_div_zero 0
		.amdhsa_exception_fp_ieee_overflow 0
		.amdhsa_exception_fp_ieee_underflow 0
		.amdhsa_exception_fp_ieee_inexact 0
		.amdhsa_exception_int_div_zero 0
	.end_amdhsa_kernel

amdhsa.kernels:
  - .agpr_count:     0
    .args:
      - .offset:         0
        .size:           296
        .value_kind:     by_value
      - .offset:         296
        .size:           4
        .value_kind:     hidden_block_count_x
      - .offset:         300
        .size:           4
        .value_kind:     hidden_block_count_y
      - .offset:         304
        .size:           4
        .value_kind:     hidden_block_count_z
      - .offset:         308
        .size:           2
        .value_kind:     hidden_group_size_x
      - .offset:         310
        .size:           2
        .value_kind:     hidden_group_size_y
      - .offset:         312
        .size:           2
        .value_kind:     hidden_group_size_z
      - .offset:         314
        .size:           2
        .value_kind:     hidden_remainder_x
      - .offset:         316
        .size:           2
        .value_kind:     hidden_remainder_y
      - .offset:         318
        .size:           2
        .value_kind:     hidden_remainder_z
      - .offset:         336
        .size:           8
        .value_kind:     hidden_global_offset_x
      - .offset:         344
        .size:           8
        .value_kind:     hidden_global_offset_y
      - .offset:         352
        .size:           8
        .value_kind:     hidden_global_offset_z
      - .offset:         360
        .size:           2
        .value_kind:     hidden_grid_dims
      - .offset:         416
        .size:           4
        .value_kind:     hidden_dynamic_lds_size
    .group_segment_fixed_size: 0
    .kernarg_segment_align: 8
    .kernarg_segment_size: 552
    .language:       OpenCL C
    .language_version:
      - 2
      - 0
    .max_flat_workgroup_size: 512
    .name:           _Z8mega_fwd4Args
    .private_segment_fixed_size: 0
    .sgpr_count:     108
    .sgpr_spill_count: 76
    .symbol:         _Z8mega_fwd4Args.kd
    .uniform_work_group_size: 1
    .uses_dynamic_stack: false
    .vgpr_count:     246
    .vgpr_spill_count: 0
    .wavefront_size: 64
